# DA fast path: second sub-tile's K fragments read after the first QK block so the post-barrier LDS burst is halved
# baseline (speedup 1.0000x reference)
; #define LAS __attribute__((address_space(3)))
; __device__ __forceinline__ void attn_fast_x2(float mr1, f32x16& L1, f32x16& oa0, f32x16& oa1, float mr2, f32x16& L2, f32x16& ob0, f32x16& ob1, ...
;     f32x16 s1, s2;
; #pragma unroll
;     for (int i = 0; i < 16; ++i) { s1[i] = -mr1; s2[i] = -mr2; }
; #pragma unroll
;     for (int ks = 0; ks < 2; ++ks) { const bf16x8 a1 = *(const LAS bf16x8*)(Ks + (kr0 + r) * KP + 16 * ks + 8 * h), a2 = *(const LAS bf16x8*)(Ks + (kr0 + r) * KP + 32 + 16 * ks + 8 * h);
;         s1 = __builtin_amdgcn_mfma_f32_32x32x16_bf16(a1, qf1[ks], s1, 0, 0, 0); s2 = __builtin_amdgcn_mfma_f32_32x32x16_bf16(a2, qf2[ks], s2, 0, 0, 0); }
;     if (need_mask) {
; #pragma unroll
;         for (int i = 0; i < 16; ++i) { const bool ok = (key0 + rowi32(i, h)) <= qpos; s1[i] = ok ? s1[i] : NEG; s2[i] = ok ? s2[i] : NEG; }
;     }
;     float p1[16], p2[16];
; #pragma unroll
;     for (int i = 0; i < 16; ++i) { p1[i] = ex2(s1[i]); p2[i] = ex2(s2[i]); }
;     const u32x4 onesu = {0x3f803f80u, 0x3f803f80u, 0x3f803f80u, 0x3f803f80u}; const bf16x8 ones = __builtin_bit_cast(bf16x8, onesu);
; #pragma unroll
;     for (int s2i = 0; s2i < 2; ++s2i) {
;         const bf16x8 pb1 = pack8(p1[8 * s2i + 0], p1[8 * s2i + 1], p1[8 * s2i + 2], p1[8 * s2i + 3], p1[8 * s2i + 4], p1[8 * s2i + 5], p1[8 * s2i + 6], p1[8 * s2i + 7]);
;         const bf16x8 pb2 = pack8(p2[8 * s2i + 0], p2[8 * s2i + 1], p2[8 * s2i + 2], p2[8 * s2i + 3], p2[8 * s2i + 4], p2[8 * s2i + 5], p2[8 * s2i + 6], p2[8 * s2i + 7]);
;         const LAS bf16_t* vp = Vt + r * VP + kr0 + 16 * s2i + 4 * h;
;         const u32x2 a0l = *(const LAS u32x2*)vp, a0h = *(const LAS u32x2*)(vp + 8);
;         const u32x2 a1l = *(const LAS u32x2*)(vp + 32 * VP), a1h = *(const LAS u32x2*)(vp + 32 * VP + 8);
;         const u32x4 v0 = {a0l.x, a0l.y, a0h.x, a0h.y}, v1 = {a1l.x, a1l.y, a1h.x, a1h.y};
;         oa0 = __builtin_amdgcn_mfma_f32_32x32x16_bf16(__builtin_bit_cast(bf16x8, v0), pb1, oa0, 0, 0, 0);
;         ob0 = __builtin_amdgcn_mfma_f32_32x32x16_bf16(__builtin_bit_cast(bf16x8, v0), pb2, ob0, 0, 0, 0);
;         oa1 = __builtin_amdgcn_mfma_f32_32x32x16_bf16(__builtin_bit_cast(bf16x8, v1), pb1, oa1, 0, 0, 0);
;         ob1 = __builtin_amdgcn_mfma_f32_32x32x16_bf16(__builtin_bit_cast(bf16x8, v1), pb2, ob1, 0, 0, 0);
;         L1 = __builtin_amdgcn_mfma_f32_32x32x16_bf16(ones, pb1, L1, 0, 0, 0);
.Lda_fast:
	v_lshl_add_u32 v189, v248, 1, v181
	v_lshlrev_b32_e32 v99, 1, v248
	v_add3_u32 v99, s18, v240, v99
	ds_read_b128 v[100:103], v189
	ds_read_b128 v[104:107], v189 offset:32
	ds_read_b128 v[108:111], v189 offset:64
	ds_read_b128 v[112:115], v189 offset:96
	v_lshl_add_u32 v98, v248, 1, v181
	v_add_u32_e32 v181, 0x3000, v98
	v_add_u32_e32 v98, 0x2000, v98
	s_waitcnt lgkmcnt(3)
	v_mfma_f32_32x32x16_bf16 v[116:131], v[100:103], v[152:155], v[206:221]
	s_waitcnt lgkmcnt(2)
	v_mfma_f32_32x32x16_bf16 v[116:131], v[104:107], v[156:159], v[116:131]
	s_waitcnt lgkmcnt(1)
	v_mfma_f32_32x32x16_bf16 v[132:147], v[108:111], v[160:163], v[190:205]
	s_waitcnt lgkmcnt(0)
	v_mfma_f32_32x32x16_bf16 v[132:147], v[112:115], v[148:151], v[132:147]
	ds_read_b128 v[182:185], v99
	ds_read_b128 v[226:229], v99 offset:32
	ds_read_b128 v[242:245], v99 offset:64
	ds_read_b128 v[172:175], v99 offset:96
	ds_read_b128 v[100:103], v98 offset:1024
	ds_read_b128 v[104:107], v181 offset:1536
	ds_read_b128 v[108:111], v98 offset:1056
	ds_read_b128 v[112:115], v181 offset:1568
	s_nop 3
	v_exp_f32_e32 v116, v116
	v_exp_f32_e32 v117, v117
	v_exp_f32_e32 v118, v118
	v_exp_f32_e32 v119, v119
	v_exp_f32_e32 v120, v120
	v_exp_f32_e32 v121, v121
	v_exp_f32_e32 v122, v122
	v_exp_f32_e32 v123, v123
	v_cvt_pk_bf16_f32 v116, v116, v117
	v_cvt_pk_bf16_f32 v117, v118, v119
	v_cvt_pk_bf16_f32 v118, v120, v121
	v_cvt_pk_bf16_f32 v119, v122, v123
	s_waitcnt lgkmcnt(2)
	s_nop 0
	v_mfma_f32_32x32x16_bf16 v[34:49], v[100:103], v[116:119], v[34:49]
	v_exp_f32_e32 v124, v124
	v_exp_f32_e32 v125, v125
	v_exp_f32_e32 v126, v126
	v_mfma_f32_32x32x16_bf16 v[66:81], v[104:107], v[116:119], v[66:81]
	v_exp_f32_e32 v127, v127
	v_exp_f32_e32 v128, v128
	v_exp_f32_e32 v129, v129
	v_mfma_f32_32x32x16_bf16 v[2:17], v[222:225], v[116:119], v[2:17]
	v_exp_f32_e32 v130, v130
	v_exp_f32_e32 v131, v131
	v_cvt_pk_bf16_f32 v120, v124, v125
	v_cvt_pk_bf16_f32 v121, v126, v127
	v_cvt_pk_bf16_f32 v122, v128, v129
	v_cvt_pk_bf16_f32 v123, v130, v131
	s_waitcnt lgkmcnt(0)
	s_nop 0
	v_mfma_f32_32x32x16_bf16 v[34:49], v[108:111], v[120:123], v[34:49]
	v_exp_f32_e32 v132, v132
	v_exp_f32_e32 v133, v133
	v_exp_f32_e32 v134, v134
	v_mfma_f32_32x32x16_bf16 v[66:81], v[112:115], v[120:123], v[66:81]
	v_exp_f32_e32 v135, v135
	v_exp_f32_e32 v136, v136
	v_exp_f32_e32 v137, v137
	v_mfma_f32_32x32x16_bf16 v[2:17], v[222:225], v[120:123], v[2:17]
	v_exp_f32_e32 v138, v138
	v_exp_f32_e32 v139, v139
	v_cvt_pk_bf16_f32 v132, v132, v133
	v_cvt_pk_bf16_f32 v133, v134, v135
	v_mfma_f32_32x32x16_bf16 v[116:131], v[182:185], v[152:155], v[206:221]
	v_cvt_pk_bf16_f32 v134, v136, v137
	v_cvt_pk_bf16_f32 v135, v138, v139
	v_exp_f32_e32 v140, v140
	v_exp_f32_e32 v141, v141
	v_mfma_f32_32x32x16_bf16 v[116:131], v[226:229], v[156:159], v[116:131]
	v_exp_f32_e32 v142, v142
	v_exp_f32_e32 v143, v143
	v_exp_f32_e32 v144, v144
	ds_read_b128 v[182:185], v98 offset:1088
	ds_read_b128 v[226:229], v181 offset:1600
	v_mfma_f32_32x32x16_bf16 v[82:97], v[100:103], v[132:135], v[82:97]
	v_exp_f32_e32 v145, v145
	v_exp_f32_e32 v146, v146
	v_exp_f32_e32 v147, v147
	v_mfma_f32_32x32x16_bf16 v[50:65], v[104:107], v[132:135], v[50:65]
	v_cvt_pk_bf16_f32 v136, v140, v141
	v_cvt_pk_bf16_f32 v137, v142, v143
	v_cvt_pk_bf16_f32 v138, v144, v145
	v_cvt_pk_bf16_f32 v139, v146, v147
	ds_read_b128 v[100:103], v98 offset:1120
	ds_read_b128 v[104:107], v181 offset:1632
	v_mfma_f32_32x32x16_bf16 v[18:33], v[222:225], v[132:135], v[18:33]
	v_exp_f32_e32 v116, v116
	v_exp_f32_e32 v117, v117
	v_exp_f32_e32 v118, v118
	v_mfma_f32_32x32x16_bf16 v[82:97], v[108:111], v[136:139], v[82:97]
	v_exp_f32_e32 v119, v119
	v_exp_f32_e32 v120, v120
	v_exp_f32_e32 v121, v121
	v_mfma_f32_32x32x16_bf16 v[50:65], v[112:115], v[136:139], v[50:65]
	v_exp_f32_e32 v122, v122
	v_exp_f32_e32 v123, v123
	v_cvt_pk_bf16_f32 v116, v116, v117
	v_cvt_pk_bf16_f32 v117, v118, v119
	v_mfma_f32_32x32x16_bf16 v[18:33], v[222:225], v[136:139], v[18:33]
	v_cvt_pk_bf16_f32 v118, v120, v121
	v_cvt_pk_bf16_f32 v119, v122, v123
	v_exp_f32_e32 v124, v124
	v_exp_f32_e32 v125, v125
	v_mfma_f32_32x32x16_bf16 v[132:147], v[242:245], v[160:163], v[190:205]
	v_exp_f32_e32 v126, v126
	v_exp_f32_e32 v127, v127
	v_exp_f32_e32 v128, v128
	v_mfma_f32_32x32x16_bf16 v[132:147], v[172:175], v[148:151], v[132:147]
	v_exp_f32_e32 v129, v129
	v_exp_f32_e32 v130, v130
	v_exp_f32_e32 v131, v131
	s_waitcnt lgkmcnt(2)
	v_mfma_f32_32x32x16_bf16 v[34:49], v[182:185], v[116:119], v[34:49]
	v_cvt_pk_bf16_f32 v120, v124, v125
	v_cvt_pk_bf16_f32 v121, v126, v127
	v_cvt_pk_bf16_f32 v122, v128, v129
	v_cvt_pk_bf16_f32 v123, v130, v131
	v_mfma_f32_32x32x16_bf16 v[66:81], v[226:229], v[116:119], v[66:81]
	s_nop 1
	v_exp_f32_e32 v132, v132
	v_exp_f32_e32 v133, v133
	v_exp_f32_e32 v134, v134
	v_mfma_f32_32x32x16_bf16 v[2:17], v[222:225], v[116:119], v[2:17]
	v_exp_f32_e32 v135, v135
	v_exp_f32_e32 v136, v136
	v_exp_f32_e32 v137, v137
	s_waitcnt lgkmcnt(0)
	v_mfma_f32_32x32x16_bf16 v[34:49], v[100:103], v[120:123], v[34:49]
	v_exp_f32_e32 v138, v138
	v_exp_f32_e32 v139, v139
	v_cvt_pk_bf16_f32 v132, v132, v133
	v_cvt_pk_bf16_f32 v133, v134, v135
	v_mfma_f32_32x32x16_bf16 v[66:81], v[104:107], v[120:123], v[66:81]
	v_cvt_pk_bf16_f32 v134, v136, v137
	v_cvt_pk_bf16_f32 v135, v138, v139
	v_exp_f32_e32 v140, v140
	v_exp_f32_e32 v141, v141
	v_mfma_f32_32x32x16_bf16 v[2:17], v[222:225], v[120:123], v[2:17]
	v_exp_f32_e32 v142, v142
	v_exp_f32_e32 v143, v143
	v_exp_f32_e32 v144, v144
	v_mfma_f32_32x32x16_bf16 v[18:33], v[222:225], v[132:135], v[18:33]
	v_exp_f32_e32 v145, v145
	v_exp_f32_e32 v146, v146
	v_exp_f32_e32 v147, v147
	v_mfma_f32_32x32x16_bf16 v[82:97], v[182:185], v[132:135], v[82:97]
	v_cvt_pk_bf16_f32 v136, v140, v141
	v_cvt_pk_bf16_f32 v137, v142, v143
	v_cvt_pk_bf16_f32 v138, v144, v145
	v_cvt_pk_bf16_f32 v139, v146, v147
	v_mfma_f32_32x32x16_bf16 v[50:65], v[226:229], v[132:135], v[50:65]
	s_nop 0
	v_mfma_f32_32x32x16_bf16 v[18:33], v[222:225], v[136:139], v[18:33]
	v_mfma_f32_32x32x16_bf16 v[82:97], v[100:103], v[136:139], v[82:97]
	v_mfma_f32_32x32x16_bf16 v[50:65], v[104:107], v[136:139], v[50:65]
	s_xor_b32 s24, s20, 1
	s_mul_i32 s24, s24, 0x4800
	v_add3_u32 v189, s24, v249, v238
	s_waitcnt vmcnt(1)
	ds_write_b128 v189, v[168:171]
	v_lshl_add_u32 v189, v251, 1, s24
	s_waitcnt vmcnt(0)
	ds_write_b16 v189, v164 offset:9216
	ds_write_b16_d16_hi v189, v164 offset:9360
	ds_write_b16 v189, v165 offset:9504
	ds_write_b16_d16_hi v189, v165 offset:9648
	ds_write_b16 v189, v166 offset:9792
	ds_write_b16_d16_hi v189, v166 offset:9936
	ds_write_b16 v189, v167 offset:10080
	v_lshl_add_u32 v189, v239, 1, s24
	s_cmp_ge_u32 s21, s6
	ds_write_b16_d16_hi v189, v167 offset:9216
	s_cbranch_scc1 .Lda_fast_nofetch
	global_load_dwordx4 v[168:171], v[234:235], off
	global_load_dwordx4 v[164:167], v[236:237], off
